# v20: v18 plus gate_unit 16-lane sum-of-squares butterfly via DPP quad_perm/row_half_mirror/row_mirror
# baseline (speedup 1.0000x reference)
; #define LAS __attribute__((address_space(3)))
; DI unsigned pk2(float lo, float hi) { f32x2 v = {lo, hi}; bf16x2_t b = __builtin_convertvector(v, bf16x2_t); return __builtin_bit_cast(unsigned, b); }
; DI float rstd_of(float ssq, float inv_n) { return 1.0f / sqrtf(ssq * inv_n + EPS); }
; DI void gate_unit(int un, int& cached_g, const bf16_t* Z, bf16_t* H, const float* Wsl, const float* gmb, const float* gmg, LAS unsigned char* lds, int tid, int wid, int lane) {
;     ...
;     for (int i = 0; i < 4; ++i) { const int idx = tid + NTHR * i, s = idx >> 4, ch = idx & 15;
;         const u32x4 w = *(const u32x4*)(Z + (size_t)(row0 + s) * INC + 2048 + g * 128 + ch * 8); float v[8]; unpack8(w, v);
;         float ss = 0.f;
; #pragma unroll
;         for (int j = 0; j < 8; ++j) ss += v[j] * v[j];
;         ss += __shfl_xor(ss, 1); ss += __shfl_xor(ss, 2); ss += __shfl_xor(ss, 4); ss += __shfl_xor(ss, 8);
;         const float rs = rstd_of(ss, 1.0f / 128.f);
; #pragma unroll
;         for (int j = 0; j < 8; j += 2) { const unsigned pw = pk2(v[j] * rs * gmg[ch * 8 + j], v[j + 1] * rs * gmg[ch * 8 + j + 1]);
;             *(LAS bf16_t*)(Gt + (ch * 8 + j) * 272 + ((s ^ (ch << 3)) << 1)) = (bf16_t)(pw & 0xffffu); *(LAS bf16_t*)(Gt + (ch * 8 + j + 1) * 272 + ((s ^ (ch << 3)) << 1)) = (bf16_t)(pw >> 16); } }
.LBB0_1861:
	v_add_u32_e32 v0, s15, v91
	v_mov_b64_e32 v[10:11], s[28:29]
	v_mad_i64_i32 v[0:1], vcc, v0, s12, v[10:11]
	s_lshl_b32 s6, s4, 1
	v_lshl_add_u64 v[0:1], v[0:1], 0, s[6:7]
	v_mov_b32_e32 v57, v97
	v_lshl_add_u64 v[0:1], v[0:1], 0, v[56:57]
	v_add_co_u32_e32 v0, vcc, 0x1000, v0
	s_movk_i32 s95, 0x1000
	s_nop 0
	v_addc_co_u32_e32 v1, vcc, 0, v1, vcc
	v_mov_b32_e32 v146, 0x28000
	v_mov_b32_e32 v147, 0
	global_load_dwordx4 v[130:133], v[0:1], off
	v_lshl_add_u64 v[148:149], v[146:147], 0, v[0:1]
	global_load_dwordx4 v[134:137], v[148:149], off
	v_lshl_add_u64 v[148:149], v[146:147], 1, v[0:1]
	global_load_dwordx4 v[138:141], v[148:149], off
	v_lshl_add_u64 v[148:149], v[146:147], 0, v[148:149]
	global_load_dwordx4 v[142:145], v[148:149], off
	v_ashrrev_i32_e32 v75, 31, v74
	v_mov_b32_e32 v116, v85
	s_waitcnt vmcnt(0)
	v_mov_b64_e32 v[0:1], v[130:131]
	v_mov_b64_e32 v[2:3], v[132:133]
	v_and_b32_e32 v12, 0xffff0000, v2
	v_lshlrev_b32_e32 v13, 16, v2
	v_and_b32_e32 v16, 0xffff0000, v3
	v_lshlrev_b32_e32 v17, 16, v3
	global_load_dwordx4 v[2:5], v[52:53], off offset:16
	global_load_dwordx4 v[6:9], v[52:53], off
	v_lshlrev_b32_e32 v20, 16, v0
	v_and_b32_e32 v21, 0xffff0000, v0
	v_pk_mul_f32 v[22:23], v[20:21], v[20:21]
	v_lshlrev_b32_e32 v24, 16, v1
	v_and_b32_e32 v25, 0xffff0000, v1
	v_pk_mul_f32 v[0:1], v[24:25], v[24:25]
	v_add_f32_e32 v22, v22, v23
	v_add_f32_e32 v0, v0, v22
	v_pk_mul_f32 v[14:15], v[12:13], v[12:13]
	v_add_f32_e32 v0, v1, v0
	v_add_f32_e32 v0, v15, v0
	v_pk_mul_f32 v[18:19], v[16:17], v[16:17]
	v_add_f32_e32 v0, v14, v0
	v_add_f32_e32 v0, v19, v0
	v_add_f32_e32 v0, v18, v0
	s_waitcnt lgkmcnt(0)
	s_nop 1
	v_add_f32_dpp v0, v0, v0 quad_perm:[1,0,3,2] row_mask:0xf bank_mask:0xf
	s_waitcnt lgkmcnt(0)
	s_nop 1
	v_add_f32_dpp v0, v0, v0 quad_perm:[2,3,0,1] row_mask:0xf bank_mask:0xf
	s_waitcnt lgkmcnt(0)
	s_nop 1
	v_add_f32_dpp v0, v0, v0 row_half_mirror row_mask:0xf bank_mask:0xf
	s_waitcnt lgkmcnt(0)
	s_nop 1
	v_add_f32_dpp v0, v0, v0 row_mirror row_mask:0xf bank_mask:0xf
	v_fmamk_f32 v0, v0, 0x3c000000, v222
	v_cmp_gt_f32_e64 s[4:5], s13, v0
	v_mul_f32_e32 v1, 0x4f800000, v0
	s_nop 0
	v_cndmask_b32_e64 v1, v0, v1, s[4:5]
	v_sqrt_f32_e32 v14, v1
	v_mov_b32_e32 v0, 0
	v_mov_b32_e32 v28, v0
	v_mov_b32_e32 v29, v0
	v_add_u32_e32 v15, -1, v14
	v_fma_f32 v18, -v15, v14, v1
	v_cmp_ge_f32_e32 vcc, 0, v18
	v_add_u32_e32 v18, 1, v14
	v_mov_b32_e32 v30, v0
	v_cndmask_b32_e32 v15, v14, v15, vcc
	v_fma_f32 v14, -v18, v14, v1
	v_cmp_lt_f32_e32 vcc, 0, v14
	v_mov_b32_e32 v31, v0
	s_nop 0
	v_cndmask_b32_e32 v14, v15, v18, vcc
	v_mul_f32_e32 v15, 0x37800000, v14
	v_cndmask_b32_e64 v14, v14, v15, s[4:5]
	v_cmp_class_f32_e32 vcc, v1, v223
	s_nop 1
	v_cndmask_b32_e32 v1, v14, v1, vcc
	v_div_scale_f32 v14, s[4:5], v1, v1, 1.0
	v_rcp_f32_e32 v15, v14
	s_nop 0
	v_fma_f32 v18, -v14, v15, 1.0
	v_fmac_f32_e32 v15, v18, v15
	v_div_scale_f32 v18, vcc, 1.0, v1, 1.0
	v_mul_f32_e32 v19, v18, v15
	v_fma_f32 v22, -v14, v19, v18
	v_fmac_f32_e32 v19, v22, v15
	v_fma_f32 v14, -v14, v19, v18
	v_div_fmas_f32 v14, v14, v15, v19
	v_div_fixup_f32 v14, v14, v1, 1.0
	v_pk_mul_f32 v[18:19], v[14:15], v[20:21] op_sel_hi:[0,1]
	s_waitcnt vmcnt(0)
	v_pk_mul_f32 v[18:19], v[6:7], v[18:19]
	v_add_u32_e32 v15, v92, v93
	v_cvt_pk_bf16_f32 v1, v18, v19
	v_pk_mul_f32 v[18:19], v[14:15], v[24:25] op_sel_hi:[0,1]
	v_pk_mul_f32 v[18:19], v[8:9], v[18:19]
	v_pk_mul_f32 v[12:13], v[14:15], v[12:13] op_sel_hi:[0,1]
	ds_write_b16 v15, v1 offset:34816
	ds_write_b16_d16_hi v15, v1 offset:35088
	v_cvt_pk_bf16_f32 v1, v18, v19
	v_add_u32_e32 v18, v92, v94
	v_pk_mul_f32 v[12:13], v[2:3], v[12:13] op_sel:[0,1] op_sel_hi:[1,0]
	ds_write_b16 v18, v1 offset:34816
	ds_write_b16_d16_hi v15, v1 offset:35632
	v_cvt_pk_bf16_f32 v1, v12, v13
	v_pk_mul_f32 v[12:13], v[14:15], v[16:17] op_sel_hi:[0,1]
	v_pk_mul_f32 v[12:13], v[4:5], v[12:13] op_sel:[0,1] op_sel_hi:[1,0]
	ds_write_b16 v18, v1 offset:35360
	ds_write_b16_d16_hi v15, v1 offset:36176
	v_cvt_pk_bf16_f32 v1, v12, v13
	ds_write_b16 v18, v1 offset:35904
	ds_write_b16_d16_hi v15, v1 offset:36720
	v_add_u32_e32 v1, s15, v102
	v_mad_i64_i32 v[12:13], s[4:5], v1, s12, v[10:11]
	v_lshl_add_u64 v[12:13], v[12:13], 0, s[6:7]
	v_lshl_add_u64 v[12:13], v[12:13], 0, v[56:57]
	v_add_co_u32_e32 v12, vcc, s95, v12
	s_nop 1
	v_addc_co_u32_e32 v13, vcc, 0, v13, vcc
	v_mov_b64_e32 v[12:13], v[134:135]
	v_mov_b64_e32 v[14:15], v[136:137]
	v_lshlrev_b32_e32 v22, 16, v12
	v_and_b32_e32 v23, 0xffff0000, v12
	v_pk_mul_f32 v[24:25], v[22:23], v[22:23]
	v_lshlrev_b32_e32 v12, 16, v13
	v_and_b32_e32 v13, 0xffff0000, v13
	v_pk_mul_f32 v[26:27], v[12:13], v[12:13]
	v_add_f32_e32 v1, v24, v25
	v_and_b32_e32 v16, 0xffff0000, v14
	v_lshlrev_b32_e32 v17, 16, v14
	v_add_f32_e32 v1, v26, v1
	v_pk_mul_f32 v[18:19], v[16:17], v[16:17]
	v_add_f32_e32 v1, v27, v1
	v_and_b32_e32 v14, 0xffff0000, v15
	v_lshlrev_b32_e32 v15, 16, v15
	v_add_f32_e32 v1, v19, v1
	v_pk_mul_f32 v[20:21], v[14:15], v[14:15]
	v_add_f32_e32 v1, v18, v1
	v_add_f32_e32 v1, v21, v1
	v_add_f32_e32 v1, v20, v1
	s_waitcnt lgkmcnt(0)
	s_nop 1
	v_add_f32_dpp v1, v1, v1 quad_perm:[1,0,3,2] row_mask:0xf bank_mask:0xf
	s_waitcnt lgkmcnt(0)
	s_nop 1
	v_add_f32_dpp v1, v1, v1 quad_perm:[2,3,0,1] row_mask:0xf bank_mask:0xf
	s_waitcnt lgkmcnt(0)
	s_nop 1
	v_add_f32_dpp v1, v1, v1 row_half_mirror row_mask:0xf bank_mask:0xf
	s_waitcnt lgkmcnt(0)
; #define LAS __attribute__((address_space(3)))
; DI unsigned pk2(float lo, float hi) { f32x2 v = {lo, hi}; bf16x2_t b = __builtin_convertvector(v, bf16x2_t); return __builtin_bit_cast(unsigned, b); }
; DI float rstd_of(float ssq, float inv_n) { return 1.0f / sqrtf(ssq * inv_n + EPS); }
; DI void gate_unit(int un, int& cached_g, const bf16_t* Z, bf16_t* H, const float* Wsl, const float* gmb, const float* gmg, LAS unsigned char* lds, int tid, int wid, int lane) {
;     ...
;     for (int i = 0; i < 4; ++i) { const int idx = tid + NTHR * i, s = idx >> 4, ch = idx & 15;
;         const u32x4 w = *(const u32x4*)(Z + (size_t)(row0 + s) * INC + 2048 + g * 128 + ch * 8); float v[8]; unpack8(w, v);
;         float ss = 0.f;
; #pragma unroll
;         for (int j = 0; j < 8; ++j) ss += v[j] * v[j];
;         ss += __shfl_xor(ss, 1); ss += __shfl_xor(ss, 2); ss += __shfl_xor(ss, 4); ss += __shfl_xor(ss, 8);
;         const float rs = rstd_of(ss, 1.0f / 128.f);
; #pragma unroll
;         for (int j = 0; j < 8; j += 2) { const unsigned pw = pk2(v[j] * rs * gmg[ch * 8 + j], v[j + 1] * rs * gmg[ch * 8 + j + 1]);
;             *(LAS bf16_t*)(Gt + (ch * 8 + j) * 272 + ((s ^ (ch << 3)) << 1)) = (bf16_t)(pw & 0xffffu); *(LAS bf16_t*)(Gt + (ch * 8 + j + 1) * 272 + ((s ^ (ch << 3)) << 1)) = (bf16_t)(pw >> 16); } }
;     __syncthreads();
;     f32x16 acc[2];
; #pragma unroll
;     for (int i = 0; i < 16; ++i) { acc[0][i] = 0.f; acc[1][i] = 0.f; }
	s_nop 1
	v_add_f32_dpp v1, v1, v1 row_mirror row_mask:0xf bank_mask:0xf
	v_fmamk_f32 v1, v1, 0x3c000000, v222
	v_rsq_f32_e32 v18, v1
	s_nop 0
	v_mul_f32_e32 v19, v1, v18
	v_fma_f32 v19, -v19, v18, 1.0
	v_mul_f32_e32 v19, 0.5, v19
	v_fmac_f32_e32 v18, v19, v18
	v_pk_mul_f32 v[20:21], v[18:19], v[22:23] op_sel_hi:[0,1]
	v_add_u32_e32 v19, v103, v93
	v_pk_mul_f32 v[20:21], v[6:7], v[20:21]
	v_pk_mul_f32 v[12:13], v[18:19], v[12:13] op_sel_hi:[0,1]
	v_cvt_pk_bf16_f32 v1, v20, v21
	v_pk_mul_f32 v[12:13], v[8:9], v[12:13]
	ds_write_b16 v19, v1 offset:34816
	ds_write_b16_d16_hi v19, v1 offset:35088
	v_cvt_pk_bf16_f32 v1, v12, v13
	v_pk_mul_f32 v[12:13], v[18:19], v[16:17] op_sel_hi:[0,1]
	v_add_u32_e32 v20, v103, v94
	v_pk_mul_f32 v[12:13], v[2:3], v[12:13] op_sel:[0,1] op_sel_hi:[1,0]
	ds_write_b16 v20, v1 offset:34816
	ds_write_b16_d16_hi v19, v1 offset:35632
	v_cvt_pk_bf16_f32 v1, v12, v13
	v_pk_mul_f32 v[12:13], v[18:19], v[14:15] op_sel_hi:[0,1]
	v_pk_mul_f32 v[12:13], v[4:5], v[12:13] op_sel:[0,1] op_sel_hi:[1,0]
	ds_write_b16 v20, v1 offset:35360
	ds_write_b16_d16_hi v19, v1 offset:36176
	v_cvt_pk_bf16_f32 v1, v12, v13
	ds_write_b16 v20, v1 offset:35904
	ds_write_b16_d16_hi v19, v1 offset:36720
	v_add_u32_e32 v1, s15, v104
	v_mad_i64_i32 v[12:13], s[4:5], v1, s12, v[10:11]
	v_lshl_add_u64 v[12:13], v[12:13], 0, s[6:7]
	v_lshl_add_u64 v[12:13], v[12:13], 0, v[56:57]
	v_add_co_u32_e32 v12, vcc, s95, v12
	s_nop 1
	v_addc_co_u32_e32 v13, vcc, 0, v13, vcc
	v_mov_b64_e32 v[12:13], v[138:139]
	v_mov_b64_e32 v[14:15], v[140:141]
	v_lshlrev_b32_e32 v22, 16, v12
	v_and_b32_e32 v23, 0xffff0000, v12
	v_pk_mul_f32 v[24:25], v[22:23], v[22:23]
	v_lshlrev_b32_e32 v12, 16, v13
	v_and_b32_e32 v13, 0xffff0000, v13
	v_pk_mul_f32 v[26:27], v[12:13], v[12:13]
	v_add_f32_e32 v1, v24, v25
	v_and_b32_e32 v16, 0xffff0000, v14
	v_lshlrev_b32_e32 v17, 16, v14
	v_add_f32_e32 v1, v26, v1
	v_pk_mul_f32 v[18:19], v[16:17], v[16:17]
	v_add_f32_e32 v1, v27, v1
	v_and_b32_e32 v14, 0xffff0000, v15
	v_lshlrev_b32_e32 v15, 16, v15
	v_add_f32_e32 v1, v19, v1
	v_pk_mul_f32 v[20:21], v[14:15], v[14:15]
	v_add_f32_e32 v1, v18, v1
	v_add_f32_e32 v1, v21, v1
	v_add_f32_e32 v1, v20, v1
	v_mov_b32_e32 v26, v0
	v_mov_b32_e32 v27, v0
	s_waitcnt lgkmcnt(0)
	s_nop 1
	v_add_f32_dpp v1, v1, v1 quad_perm:[1,0,3,2] row_mask:0xf bank_mask:0xf
	s_waitcnt lgkmcnt(0)
	s_nop 1
	v_add_f32_dpp v1, v1, v1 quad_perm:[2,3,0,1] row_mask:0xf bank_mask:0xf
	s_waitcnt lgkmcnt(0)
	s_nop 1
	v_add_f32_dpp v1, v1, v1 row_half_mirror row_mask:0xf bank_mask:0xf
	s_waitcnt lgkmcnt(0)
	s_nop 1
	v_add_f32_dpp v1, v1, v1 row_mirror row_mask:0xf bank_mask:0xf
	v_fmamk_f32 v1, v1, 0x3c000000, v222
	v_rsq_f32_e32 v18, v1
	s_nop 0
	v_mul_f32_e32 v19, v1, v18
	v_fma_f32 v19, -v19, v18, 1.0
	v_mul_f32_e32 v19, 0.5, v19
	v_fmac_f32_e32 v18, v19, v18
	v_pk_mul_f32 v[20:21], v[18:19], v[22:23] op_sel_hi:[0,1]
	v_add_u32_e32 v19, v105, v93
	v_pk_mul_f32 v[20:21], v[6:7], v[20:21]
	v_pk_mul_f32 v[12:13], v[18:19], v[12:13] op_sel_hi:[0,1]
	v_cvt_pk_bf16_f32 v1, v20, v21
	v_pk_mul_f32 v[12:13], v[8:9], v[12:13]
	ds_write_b16 v19, v1 offset:34816
	ds_write_b16_d16_hi v19, v1 offset:35088
	v_cvt_pk_bf16_f32 v1, v12, v13
	v_pk_mul_f32 v[12:13], v[18:19], v[16:17] op_sel_hi:[0,1]
	v_add_u32_e32 v20, v105, v94
	v_pk_mul_f32 v[12:13], v[2:3], v[12:13] op_sel:[0,1] op_sel_hi:[1,0]
	ds_write_b16 v20, v1 offset:34816
	ds_write_b16_d16_hi v19, v1 offset:35632
	v_cvt_pk_bf16_f32 v1, v12, v13
	v_pk_mul_f32 v[12:13], v[18:19], v[14:15] op_sel_hi:[0,1]
	v_pk_mul_f32 v[12:13], v[4:5], v[12:13] op_sel:[0,1] op_sel_hi:[1,0]
	ds_write_b16 v20, v1 offset:35360
	ds_write_b16_d16_hi v19, v1 offset:36176
	v_cvt_pk_bf16_f32 v1, v12, v13
	ds_write_b16 v20, v1 offset:35904
	ds_write_b16_d16_hi v19, v1 offset:36720
	v_add_u32_e32 v1, s15, v106
	v_mad_i64_i32 v[10:11], s[4:5], v1, s12, v[10:11]
	v_lshl_add_u64 v[10:11], v[10:11], 0, s[6:7]
	v_lshl_add_u64 v[10:11], v[10:11], 0, v[56:57]
	v_add_co_u32_e32 v10, vcc, s95, v10
	v_mov_b32_e32 v57, v95
	s_nop 0
	v_addc_co_u32_e32 v11, vcc, 0, v11, vcc
	v_mov_b64_e32 v[10:11], v[142:143]
	v_mov_b64_e32 v[12:13], v[144:145]
	v_lshlrev_b32_e32 v20, 16, v10
	v_and_b32_e32 v21, 0xffff0000, v10
	v_pk_mul_f32 v[22:23], v[20:21], v[20:21]
	v_lshlrev_b32_e32 v10, 16, v11
	v_and_b32_e32 v11, 0xffff0000, v11
	v_pk_mul_f32 v[24:25], v[10:11], v[10:11]
	v_add_f32_e32 v1, v22, v23
	v_and_b32_e32 v14, 0xffff0000, v12
	v_lshlrev_b32_e32 v15, 16, v12
	v_add_f32_e32 v1, v24, v1
	v_pk_mul_f32 v[16:17], v[14:15], v[14:15]
	v_add_f32_e32 v1, v25, v1
	v_and_b32_e32 v12, 0xffff0000, v13
	v_lshlrev_b32_e32 v13, 16, v13
	v_add_f32_e32 v1, v17, v1
	v_pk_mul_f32 v[18:19], v[12:13], v[12:13]
	v_add_f32_e32 v1, v16, v1
	v_add_f32_e32 v1, v19, v1
	v_add_f32_e32 v1, v18, v1
	v_mov_b32_e32 v23, v0
	v_mov_b32_e32 v24, v0
	v_mov_b32_e32 v25, v0
	s_waitcnt lgkmcnt(0)
	s_nop 1
	v_add_f32_dpp v1, v1, v1 quad_perm:[1,0,3,2] row_mask:0xf bank_mask:0xf
	s_waitcnt lgkmcnt(0)
	s_nop 1
	v_add_f32_dpp v1, v1, v1 quad_perm:[2,3,0,1] row_mask:0xf bank_mask:0xf
	s_waitcnt lgkmcnt(0)
	s_nop 1
	v_add_f32_dpp v1, v1, v1 row_half_mirror row_mask:0xf bank_mask:0xf
	s_waitcnt lgkmcnt(0)
	s_nop 1
	v_add_f32_dpp v1, v1, v1 row_mirror row_mask:0xf bank_mask:0xf
	v_fmamk_f32 v1, v1, 0x3c000000, v222
	v_rsq_f32_e32 v16, v1
	s_nop 0
	v_mul_f32_e32 v17, v1, v16
	v_fma_f32 v17, -v17, v16, 1.0
	v_mul_f32_e32 v17, 0.5, v17
	v_fmac_f32_e32 v16, v17, v16
	s_mov_b32 s4, s30
	v_pk_mul_f32 v[18:19], v[16:17], v[20:21] op_sel_hi:[0,1]
	v_pk_mul_f32 v[6:7], v[6:7], v[18:19]
	v_add_u32_e32 v17, v107, v93
	v_cvt_pk_bf16_f32 v1, v6, v7
	v_pk_mul_f32 v[6:7], v[16:17], v[10:11] op_sel_hi:[0,1]
	v_pk_mul_f32 v[6:7], v[8:9], v[6:7]
	ds_write_b16 v17, v1 offset:34816
	ds_write_b16_d16_hi v17, v1 offset:35088
	v_cvt_pk_bf16_f32 v1, v6, v7
	v_pk_mul_f32 v[6:7], v[16:17], v[14:15] op_sel_hi:[0,1]
	v_add_u32_e32 v8, v107, v94
	v_pk_mul_f32 v[2:3], v[2:3], v[6:7] op_sel:[0,1] op_sel_hi:[1,0]
	ds_write_b16 v8, v1 offset:34816
	ds_write_b16_d16_hi v17, v1 offset:35632
	v_cvt_pk_bf16_f32 v1, v2, v3
	v_pk_mul_f32 v[2:3], v[16:17], v[12:13] op_sel_hi:[0,1]
	v_pk_mul_f32 v[2:3], v[4:5], v[2:3] op_sel:[0,1] op_sel_hi:[1,0]
	ds_write_b16 v8, v1 offset:35360
	ds_write_b16_d16_hi v17, v1 offset:36176
	v_cvt_pk_bf16_f32 v1, v2, v3
	ds_write_b16 v8, v1 offset:35904
	ds_write_b16_d16_hi v17, v1 offset:36720
	v_mov_b32_e32 v1, v0
	v_mov_b32_e32 v2, v0
	v_mov_b32_e32 v3, v0
	v_mov_b32_e32 v4, v0
	v_mov_b32_e32 v5, v0
	v_mov_b32_e32 v6, v0
	v_mov_b32_e32 v7, v0
	v_mov_b32_e32 v8, v0
	v_mov_b32_e32 v9, v0
	v_mov_b32_e32 v10, v0
	v_mov_b32_e32 v11, v0
	v_mov_b32_e32 v12, v0
	v_mov_b32_e32 v13, v0
	v_mov_b32_e32 v14, v0
	v_mov_b32_e32 v15, v0
	v_mov_b32_e32 v16, v0
	v_mov_b32_e32 v17, v0
	v_mov_b32_e32 v18, v0
	v_mov_b32_e32 v19, v0
	v_mov_b32_e32 v20, v0
	v_mov_b32_e32 v21, v0
	v_mov_b32_e32 v22, v0
	s_waitcnt lgkmcnt(0)
	s_barrier
